# MLA attention: softmax scale folded into the q gains of the projection phase, constant shift dropped (57 of 64 v_fma per key tile removed)
# baseline (speedup 1.0000x reference)
; __device__ void phase_p3b(PRef p, int l, float* smem, int vb, int vg) {
;     ...
;   int gw = vb * 4 + wave, nw = vg * 4;
;   int h = lane >> 3, sub = lane & 7;
;   int hfB = (sub >> 1) & 1;
;   const float* qn_g = p.b_qn_g + l * 96;
;   const float* kn_g = p.b_kn_g + l * 96;
;   const float* cq_g = p.c_qn_g + l * 64;
;   const float* ck_g = p.c_kn_g + l * 64;
;   float gqN[8], gqR[4], gkN[16], gkR[4], gkRp[4], gcq[8], gck[8];
; #pragma unroll
;   for (int j = 0; j < 8; j++) { gqN[j] = qn_g[sub * 8 + j]; gcq[j] = cq_g[sub * 8 + j]; gck[j] = ck_g[sub * 8 + j]; }
; #pragma unroll
;   for (int j = 0; j < 4; j++) {
;     gqR[j] = qn_g[64 + sub * 4 + j];
;     gkR[j] = kn_g[64 + sub * 4 + j];
;     gkRp[j] = kn_g[64 + ((sub ^ 2) * 4) + j];
;   }
; #pragma unroll
;   for (int j = 0; j < 16; j++) gkN[j] = kn_g[(sub & 3) * 16 + j];
;   for (int R = gw; R < NROWS; R += nw) {
;     int tp = R % TPB;
;     bool lat = tp >= 256;
;     int t = lat ? tp - 256 : 0;
;     const bf16* zb = p.ZB + (size_t)R * 512;
;     bf16* q = p.Q + (size_t)R * 768;
;     bf16* kv = p.KV + (size_t)R * 1024;
;     bf16* kr = p.KR + (size_t)R * 256;
;     bf16* zc = p.ZC + (size_t)R * 768;
;     const float* tabB = p.ROPE + (size_t)t * 96;
;     const float* tabC = tabB + 32;
;     uint2 cq2 = *(const uint2*)(zb + lane * 4);
;     uint32_t ckv2 = *(const uint32_t*)(zb + 256 + lane * 2);
;     uint2 krO = *(const uint2*)(zb + 384 + sub * 4);
;     uint2 krP = *(const uint2*)(zb + 384 + (sub ^ 2) * 4);
;     u32x4 qN = *(const u32x4*)(q + h * 96 + sub * 8);
;     uint2 qR = *(const uint2*)(q + h * 96 + 64 + sub * 4);
;     u32x4 kv0 = *(const u32x4*)(kv + h * 128 + sub * 16);
;     u32x4 kv1 = *(const u32x4*)(kv + h * 128 + sub * 16 + 8);
;     u32x4 cqv = *(const u32x4*)(zc + h * 64 + sub * 8);
;     u32x4 ckv = *(const u32x4*)(zc + 512 + (h & 1) * 64 + sub * 8);
;     int axis = sub >> 2;
;     f32x4v tB0 = *(const f32x4v*)(tabB + 2 * (axis * 8 + (sub & 1) * 4));
;     f32x4v tB1 = *(const f32x4v*)(tabB + 2 * (axis * 8 + (sub & 1) * 4) + 4);
;     f32x4v tC[4];
; #pragma unroll
;     for (int i = 0; i < 4; i++) tC[i] = *(const f32x4v*)(tabC + 2 * (axis * 16 + (sub & 1) * 8) + 4 * i);
.LBB0_479:
	s_or_b64 exec, exec, s[4:5]
	v_mov_b32_e32 v1, v196
	s_barrier
	s_nop 0
	v_ashrrev_i32_e32 v0, 6, v1
	v_lshl_add_u32 v0, s30, 2, v0
	v_cmp_gt_i32_e32 vcc, s54, v0
	s_and_saveexec_b64 s[26:27], vcc
	s_cbranch_execz .LBB0_484
	s_load_dwordx8 s[4:11], s[34:35], 0xb8
	s_ashr_i32 s97, s96, 31
	s_lshl_b64 s[0:1], s[96:97], 2
	v_and_b32_e32 v57, 7, v1
	v_lshlrev_b32_e32 v59, 5, v57
	s_waitcnt lgkmcnt(0)
	s_add_u32 s4, s4, s0
	s_addc_u32 s5, s5, s1
	s_lshl_b32 s12, s36, 6
	s_ashr_i32 s13, s12, 31
	s_lshl_b64 s[12:13], s[12:13], 2
	s_add_u32 s8, s8, s12
	s_addc_u32 s9, s9, s13
	s_add_u32 s10, s10, s12
	s_addc_u32 s11, s11, s13
	global_load_dwordx4 v[4:7], v59, s[4:5] offset:16
	global_load_dwordx4 v[8:11], v59, s[4:5]
	global_load_dwordx4 v[12:15], v59, s[8:9] offset:16
	global_load_dwordx4 v[16:19], v59, s[8:9]
	global_load_dwordx4 v[20:23], v59, s[10:11] offset:16
	global_load_dwordx4 v[24:27], v59, s[10:11]
	s_add_u32 s0, s6, s0
	v_lshlrev_b32_e32 v2, 6, v1
	s_addc_u32 s1, s7, s1
	s_waitcnt vmcnt(18)
	v_lshlrev_b32_e32 v96, 4, v57
	v_and_b32_e32 v2, 0xc0, v2
	global_load_dwordx4 v[28:31], v96, s[4:5] offset:256
	global_load_dwordx4 v[32:35], v96, s[0:1] offset:256
	global_load_dwordx4 v[36:39], v2, s[0:1] offset:48
	global_load_dwordx4 v[40:43], v2, s[0:1] offset:32
	global_load_dwordx4 v[44:47], v2, s[0:1] offset:16
	global_load_dwordx4 v[48:51], v2, s[0:1]
	v_xor_b32_e32 v2, 32, v96
	global_load_dwordx4 v[52:55], v2, s[0:1] offset:256
	s_load_dwordx4 s[20:23], s[34:35], 0x178
	s_load_dwordx4 s[12:15], s[34:35], 0x160
	v_and_b32_e32 v62, 63, v1
	v_bfe_u32 v63, v1, 3, 3
	v_bfe_u32 v58, v1, 2, 1
	v_and_b32_e32 v60, 1, v1
	v_and_b32_e32 v1, 2, v1
	v_lshlrev_b32_e32 v56, 3, v60
	v_lshlrev_b32_e32 v60, 4, v60
	v_cmp_eq_u32_e32 vcc, 0, v1
	v_ashrrev_i32_e32 v1, 31, v0
	v_lshl_or_b32 v56, v58, 4, v56
	v_lshl_or_b32 v58, v58, 5, v60
	v_lshlrev_b64 v[60:61], 10, v[0:1]
	s_waitcnt lgkmcnt(0)
	v_lshl_add_u64 v[102:103], s[12:13], 0, v[60:61]
	v_lshlrev_b64 v[60:61], 9, v[0:1]
	v_lshl_or_b32 v60, v63, 6, v60
	s_waitcnt vmcnt(24)
	v_lshl_add_u64 v[104:105], s[22:23], 0, v[60:61]
	v_lshlrev_b64 v[60:61], 11, v[0:1]
	v_lshlrev_b32_e32 v1, 8, v63
	v_mul_u32_u24_e32 v64, 0x60, v63
	v_or3_b32 v60, v60, v1, v59
	v_lshlrev_b32_e32 v2, 7, v63
	v_cmp_gt_u32_e64 s[8:9], 16, v62
	v_lshl_or_b32 v100, v62, 3, 4
	v_lshl_or_b32 v106, v62, 2, v202
	v_lshl_add_u64 v[60:61], s[20:21], 0, v[60:61]
	v_lshlrev_b32_e32 v62, 1, v64
	v_mov_b32_e32 v63, v3
	v_lshl_add_u64 v[108:109], v[60:61], 0, 16
	v_mad_i64_i32 v[60:61], s[0:1], v0, s65, 0
	v_mad_i64_i32 v[62:63], s[0:1], v0, s65, v[62:63]
	v_readlane_b32 s0, v245, 4
	v_readlane_b32 s1, v245, 5
	v_lshlrev_b32_e32 v98, 3, v57
	s_movk_i32 s97, 0x6000
	v_lshl_add_u64 v[110:111], s[0:1], 0, v[62:63]
	s_movk_i32 s0, 0x80
	v_and_or_b32 v60, v2, s0, v60
	v_lshl_add_u64 v[60:61], s[14:15], 0, v[60:61]
	s_mov_b64 s[0:1], 0x400
	s_waitcnt vmcnt(23)
	v_lshl_add_u64 v[112:113], v[60:61], 0, s[0:1]
	v_mad_i64_i32 v[60:61], s[0:1], v0, s65, v[2:3]
	s_movk_i32 s95, 0xff
	s_movk_i32 s94, 0xe00
	v_mov_b32_e32 v99, v3
	v_mov_b32_e32 v97, v3
	v_cmp_lt_u32_e64 s[4:5], 3, v57
	v_cmp_gt_u32_e64 s[6:7], 4, v57
	v_mov_b32_e32 v101, v3
	v_mov_b32_e32 v107, v3
	v_lshl_add_u64 v[114:115], s[14:15], 0, v[60:61]
	s_waitcnt vmcnt(21)
	v_xor_b32_e32 v116, 16, v98
	v_mov_b32_e32 v117, v3
	s_mov_b64 s[14:15], 0
	v_lshlrev_b32_e32 v2, 2, v56
	v_lshlrev_b32_e32 v118, 2, v58
	s_waitcnt vmcnt(0)
	v_mul_f32_e32 v4, 0x3e16c740, v4
	v_mul_f32_e32 v5, 0x3e16c740, v5
	v_mul_f32_e32 v6, 0x3e16c740, v6
	v_mul_f32_e32 v7, 0x3e16c740, v7
	v_mul_f32_e32 v8, 0x3e16c740, v8
	v_mul_f32_e32 v9, 0x3e16c740, v9
	v_mul_f32_e32 v10, 0x3e16c740, v10
	v_mul_f32_e32 v11, 0x3e16c740, v11
	v_mul_f32_e32 v28, 0x3e16c740, v28
	v_mul_f32_e32 v29, 0x3e16c740, v29
	v_mul_f32_e32 v30, 0x3e16c740, v30
	v_mul_f32_e32 v31, 0x3e16c740, v31
	s_branch .LBB0_482

; template <int DQK> ...
;     ...
;     for (int kb = 0; kb < 4; kb++) {
; #pragma unroll
;       for (int r = 0; r < 16; r++) s[kb][r] = 0.f;
; #pragma unroll
;       for (int ks = 0; ks < NKS; ks++) {
;         bf16x8 a = *(const bf16x8*)(sm->K + (kb * 32 + (lane & 31)) * 104 + ks * 16 + hh * 8);
;         s[kb] = __builtin_amdgcn_mfma_f32_32x32x16_bf16(a, qf[ks], s[kb], 0, 0, 0);
;       }
;     }
;     float psum = 0.f;
; #pragma unroll
;     for (int kb = 0; kb < 4; kb++)
; #pragma unroll
;       for (int r = 0; r < 16; r++) {
;         float v = s[kb][r];
;         if (msk) {
;           int key = kb * 32 + (r & 3) + 8 * (r >> 2) + 4 * hh;
;           int d = (krow0 + key) - qrow;
;           if (d > 128 || d < -128) v = -1e30f;
;         }
;         float pv = __builtin_amdgcn_exp2f(__builtin_fmaf(v, scale2, -m));
;         s[kb][r] = pv;
;         psum += pv;
;       }
.LBB0_698:
	ds_read_b128 v[36:39], v227
	ds_read_b128 v[40:43], v227 offset:32
	ds_read_b128 v[52:55], v227 offset:13344
	ds_read_b128 v[230:233], v227 offset:20000
	s_addk_i32 s15, 0x80
	s_waitcnt lgkmcnt(3)
	v_mfma_f32_32x32x16_bf16 v[84:99], v[36:39], v[100:103], 0
	ds_read_b128 v[36:39], v227 offset:64
	s_add_i32 s49, s49, 1
	s_cmp_lg_u32 s14, s15
	s_waitcnt lgkmcnt(3)
	v_mfma_f32_32x32x16_bf16 v[84:99], v[40:43], v[104:107], v[84:99]
	s_waitcnt lgkmcnt(0)
	v_mfma_f32_32x32x16_bf16 v[84:99], v[36:39], v[108:111], v[84:99]
	ds_read_b128 v[36:39], v227 offset:96
	s_waitcnt lgkmcnt(0)
	v_mfma_f32_32x32x16_bf16 v[84:99], v[36:39], v[112:115], v[84:99]
	ds_read_b128 v[36:39], v227 offset:128
	s_waitcnt lgkmcnt(0)
	v_mfma_f32_32x32x16_bf16 v[84:99], v[36:39], v[116:119], v[84:99]
	ds_read_b128 v[36:39], v227 offset:160
	s_waitcnt lgkmcnt(0)
	v_mfma_f32_32x32x16_bf16 v[84:99], v[36:39], v[120:123], v[84:99]
	ds_read_b128 v[36:39], v227 offset:6656
	s_waitcnt lgkmcnt(0)
	v_mfma_f32_32x32x16_bf16 v[68:83], v[36:39], v[100:103], 0
	ds_read_b128 v[36:39], v227 offset:6688
	s_nop 7
	v_exp_f32_e32 v229, v84
	s_nop 0
	v_add_f32_e32 v84, 0, v229
	s_waitcnt lgkmcnt(0)
	v_mfma_f32_32x32x16_bf16 v[68:83], v[36:39], v[104:107], v[68:83]
	ds_read_b128 v[36:39], v227 offset:6720
	s_waitcnt lgkmcnt(0)
	v_mfma_f32_32x32x16_bf16 v[68:83], v[36:39], v[108:111], v[68:83]
	ds_read_b128 v[36:39], v227 offset:6752
	s_waitcnt lgkmcnt(0)
	v_mfma_f32_32x32x16_bf16 v[68:83], v[36:39], v[112:115], v[68:83]
	ds_read_b128 v[36:39], v227 offset:6784
	s_waitcnt lgkmcnt(0)
	v_mfma_f32_32x32x16_bf16 v[68:83], v[36:39], v[116:119], v[68:83]
	ds_read_b128 v[36:39], v227 offset:6816
	s_waitcnt lgkmcnt(0)
	v_mfma_f32_32x32x16_bf16 v[68:83], v[36:39], v[120:123], v[68:83]
	ds_read_b128 v[36:39], v227 offset:13312
	s_waitcnt lgkmcnt(0)
	v_mfma_f32_32x32x16_bf16 v[36:51], v[36:39], v[100:103], 0
	s_nop 8
	v_mfma_f32_32x32x16_bf16 v[36:51], v[52:55], v[104:107], v[36:51]
	ds_read_b128 v[52:55], v227 offset:13376
	s_waitcnt lgkmcnt(0)
	v_mfma_f32_32x32x16_bf16 v[36:51], v[52:55], v[108:111], v[36:51]
	ds_read_b128 v[52:55], v227 offset:13408
	s_waitcnt lgkmcnt(0)
	v_mfma_f32_32x32x16_bf16 v[36:51], v[52:55], v[112:115], v[36:51]
	ds_read_b128 v[52:55], v227 offset:13440
	s_waitcnt lgkmcnt(0)
	v_mfma_f32_32x32x16_bf16 v[36:51], v[52:55], v[116:119], v[36:51]
	ds_read_b128 v[52:55], v227 offset:13472
	s_waitcnt lgkmcnt(0)
	v_mfma_f32_32x32x16_bf16 v[36:51], v[52:55], v[120:123], v[36:51]
	ds_read_b128 v[52:55], v227 offset:19968
	s_waitcnt lgkmcnt(0)
	v_mfma_f32_32x32x16_bf16 v[52:67], v[52:55], v[100:103], 0
	s_nop 8
	v_mfma_f32_32x32x16_bf16 v[52:67], v[230:233], v[104:107], v[52:67]
	ds_read_b128 v[230:233], v227 offset:20032
	s_waitcnt lgkmcnt(0)
	v_mfma_f32_32x32x16_bf16 v[52:67], v[230:233], v[108:111], v[52:67]
	ds_read_b128 v[230:233], v227 offset:20064
	s_waitcnt lgkmcnt(0)
	v_mfma_f32_32x32x16_bf16 v[52:67], v[230:233], v[112:115], v[52:67]
	ds_read_b128 v[230:233], v227 offset:20096
	s_waitcnt lgkmcnt(0)
	v_mfma_f32_32x32x16_bf16 v[52:67], v[230:233], v[116:119], v[52:67]
	ds_read_b128 v[230:233], v227 offset:20128
	s_waitcnt lgkmcnt(0)
	v_mfma_f32_32x32x16_bf16 v[52:67], v[230:233], v[120:123], v[52:67]
	v_exp_f32_e32 v230, v85
	v_exp_f32_e32 v231, v86
	v_exp_f32_e32 v232, v87
	v_exp_f32_e32 v233, v88
	v_add_f32_e32 v84, v230, v84
	v_exp_f32_e32 v234, v89
	v_add_f32_e32 v84, v231, v84
	v_exp_f32_e32 v235, v90
	v_add_f32_e32 v84, v232, v84
	v_exp_f32_e32 v236, v91
	v_add_f32_e32 v84, v233, v84
	v_exp_f32_e32 v91, v92
	v_add_f32_e32 v84, v234, v84
	v_exp_f32_e32 v237, v93
	v_add_f32_e32 v84, v235, v84
	v_exp_f32_e32 v94, v94
	v_add_f32_e32 v84, v236, v84
	v_exp_f32_e32 v95, v95
	v_add_f32_e32 v84, v91, v84
	v_exp_f32_e32 v96, v96
	v_add_f32_e32 v84, v237, v84
	v_exp_f32_e32 v97, v97
	v_add_f32_e32 v84, v94, v84
	v_exp_f32_e32 v98, v98
	v_add_f32_e32 v84, v95, v84
	v_exp_f32_e32 v99, v99
	v_add_f32_e32 v84, v96, v84
	v_exp_f32_e32 v85, v68
	v_add_f32_e32 v84, v97, v84
	v_exp_f32_e32 v87, v69
	v_add_f32_e32 v84, v98, v84
	v_exp_f32_e32 v89, v70
	v_add_f32_e32 v84, v99, v84
	v_exp_f32_e32 v92, v71
	v_add_f32_e32 v68, v85, v84
	v_exp_f32_e32 v238, v72
	v_add_f32_e32 v68, v87, v68
	v_exp_f32_e32 v239, v73
	v_add_f32_e32 v68, v89, v68
	v_exp_f32_e32 v240, v74
	v_add_f32_e32 v68, v92, v68
	v_exp_f32_e32 v241, v75
	v_add_f32_e32 v68, v238, v68
	v_exp_f32_e32 v73, v76
	v_add_f32_e32 v68, v239, v68
	v_exp_f32_e32 v84, v77
	v_add_f32_e32 v68, v240, v68
	v_exp_f32_e32 v86, v78
	v_add_f32_e32 v68, v241, v68
	v_exp_f32_e32 v88, v79
	v_add_f32_e32 v68, v73, v68
	v_exp_f32_e32 v90, v80
	v_add_f32_e32 v68, v84, v68
	v_exp_f32_e32 v93, v81
	v_exp_f32_e32 v72, v37
	v_add_f32_e32 v68, v86, v68
	v_exp_f32_e32 v242, v82
	v_exp_f32_e32 v75, v38
	v_add_f32_e32 v68, v88, v68
	v_exp_f32_e32 v243, v83
	v_exp_f32_e32 v77, v39
	v_add_f32_e32 v68, v90, v68
	v_exp_f32_e32 v71, v36
	v_exp_f32_e32 v79, v40
	v_add_f32_e32 v68, v93, v68
	v_exp_f32_e32 v81, v41
	v_add_f32_e32 v68, v242, v68
	v_exp_f32_e32 v83, v42
	v_add_f32_e32 v68, v243, v68
	v_exp_f32_e32 v244, v43
	v_add_f32_e32 v36, v71, v68
	v_exp_f32_e32 v68, v44
	v_exp_f32_e32 v44, v58
	v_exp_f32_e32 v69, v45
	v_mov_b32_e32 v37, v46
	v_exp_f32_e32 v46, v59
	v_mov_b32_e32 v43, v60
	v_mov_b32_e32 v45, v61
	ds_read_b64_tr_b16 v[58:59], v228 offset:26624
	ds_read_b64_tr_b16 v[60:61], v228 offset:28160
	v_mov_b32_e32 v38, v54
	v_mov_b32_e32 v40, v55
	v_mov_b32_e32 v41, v56
	v_mov_b32_e32 v42, v57
	v_cvt_pk_bf16_f32 v54, v229, v230
	v_cvt_pk_bf16_f32 v55, v231, v232
	v_cvt_pk_bf16_f32 v56, v233, v234
	v_cvt_pk_bf16_f32 v57, v235, v236
	v_exp_f32_e32 v70, v37
	s_waitcnt lgkmcnt(0)
; template <int DQK> ...
;     ...
;         float pv = __builtin_amdgcn_exp2f(__builtin_fmaf(v, scale2, -m));
;         s[kb][r] = pv;
;         psum += pv;
;       }
;     lsum += psum;
; #pragma unroll
;     for (int kb = 0; kb < 4; kb++)
; #pragma unroll
;       for (int s2 = 0; s2 < 2; s2++) {
;         u32x4 pfu;
; #pragma unroll
;         for (int j = 0; j < 4; j++) pfu[j] = pack2(s[kb][8 * s2 + 2 * j], s[kb][8 * s2 + 2 * j + 1]);
;         bf16x8 pf = __builtin_bit_cast(bf16x8, pfu);
; #pragma unroll
;         for (int db = 0; db < 2; db++) {
;           typedef __attribute__((address_space(3))) s16x4* lds_s4p;
;           const bf16* vb = sm->V + (kb * 32 + 16 * s2 + 4 * hh + ((lane & 15) >> 2)) * 96 + db * 32 + 16 * ((lane >> 4) & 1) + 4 * (lane & 3);
;           s16x4 lo = __builtin_amdgcn_ds_read_tr16_b64_v4i16((lds_s4p)vb);
;           s16x4 hi = __builtin_amdgcn_ds_read_tr16_b64_v4i16((lds_s4p)(vb + 8 * 96));
;           bf16x8 vf;
;           vf[0] = lo[0]; vf[1] = lo[1]; vf[2] = lo[2]; vf[3] = lo[3];
;           vf[4] = hi[0]; vf[5] = hi[1]; vf[6] = hi[2]; vf[7] = hi[3];
;           o[db] = __builtin_amdgcn_mfma_f32_32x32x16_bf16(vf, pf, o[db], 0, 0, 0);
;         }
;       }
	v_mfma_f32_32x32x16_bf16 v[20:35], v[58:61], v[54:57], v[20:35]
	ds_read_b64_tr_b16 v[58:59], v228 offset:26688
	ds_read_b64_tr_b16 v[60:61], v228 offset:28224
	v_exp_f32_e32 v74, v47
	v_exp_f32_e32 v76, v48
	v_exp_f32_e32 v78, v49
	s_waitcnt lgkmcnt(0)
	v_mfma_f32_32x32x16_bf16 v[4:19], v[58:61], v[54:57], v[4:19]
	ds_read_b64_tr_b16 v[58:59], v228 offset:29696
	ds_read_b64_tr_b16 v[60:61], v228 offset:31232
	v_cvt_pk_bf16_f32 v54, v91, v237
	v_cvt_pk_bf16_f32 v55, v94, v95
	v_cvt_pk_bf16_f32 v56, v96, v97
	v_cvt_pk_bf16_f32 v57, v98, v99
	v_exp_f32_e32 v80, v50
	s_waitcnt lgkmcnt(0)
	v_mfma_f32_32x32x16_bf16 v[20:35], v[58:61], v[54:57], v[20:35]
	ds_read_b64_tr_b16 v[58:59], v228 offset:29760
	ds_read_b64_tr_b16 v[60:61], v228 offset:31296
	v_exp_f32_e32 v82, v51
	v_add_f32_e32 v36, v72, v36
	v_add_f32_e32 v36, v75, v36
	v_add_f32_e32 v36, v77, v36
	v_add_f32_e32 v36, v79, v36
	s_waitcnt lgkmcnt(0)
	v_mfma_f32_32x32x16_bf16 v[4:19], v[58:61], v[54:57], v[4:19]
	ds_read_b64_tr_b16 v[58:59], v228 offset:32768
	ds_read_b64_tr_b16 v[60:61], v228 offset:34304
	v_cvt_pk_bf16_f32 v54, v85, v87
	v_cvt_pk_bf16_f32 v55, v89, v92
	v_cvt_pk_bf16_f32 v56, v238, v239
	v_cvt_pk_bf16_f32 v57, v240, v241
	v_exp_f32_e32 v39, v52
	s_waitcnt lgkmcnt(0)
	v_mfma_f32_32x32x16_bf16 v[20:35], v[58:61], v[54:57], v[20:35]
	ds_read_b64_tr_b16 v[58:59], v228 offset:32832
	ds_read_b64_tr_b16 v[60:61], v228 offset:34368
	v_add_f32_e32 v36, v81, v36
	v_exp_f32_e32 v37, v53
	v_exp_f32_e32 v38, v38
	v_exp_f32_e32 v40, v40
	v_exp_f32_e32 v41, v41
	v_exp_f32_e32 v42, v42
	s_waitcnt lgkmcnt(0)
	v_mfma_f32_32x32x16_bf16 v[4:19], v[58:61], v[54:57], v[4:19]
	ds_read_b64_tr_b16 v[58:59], v228 offset:35840
	ds_read_b64_tr_b16 v[60:61], v228 offset:37376
	v_cvt_pk_bf16_f32 v54, v73, v84
	v_cvt_pk_bf16_f32 v55, v86, v88
	v_cvt_pk_bf16_f32 v56, v90, v93
	v_cvt_pk_bf16_f32 v57, v242, v243
	v_add_f32_e32 v36, v83, v36
	v_add_f32_e32 v36, v244, v36
	s_waitcnt lgkmcnt(0)
	v_mfma_f32_32x32x16_bf16 v[20:35], v[58:61], v[54:57], v[20:35]
	ds_read_b64_tr_b16 v[58:59], v228 offset:35904
	ds_read_b64_tr_b16 v[60:61], v228 offset:37440
	v_add_f32_e32 v36, v68, v36
	v_add_f32_e32 v36, v69, v36
	v_add_f32_e32 v36, v70, v36
	v_add_f32_e32 v36, v74, v36
	v_add_f32_e32 v36, v76, v36
	s_waitcnt lgkmcnt(0)
	v_mfma_f32_32x32x16_bf16 v[4:19], v[58:61], v[54:57], v[4:19]
	ds_read_b64_tr_b16 v[58:59], v228 offset:38912
	ds_read_b64_tr_b16 v[60:61], v228 offset:40448
	v_cvt_pk_bf16_f32 v54, v71, v72
	v_cvt_pk_bf16_f32 v55, v75, v77
	v_cvt_pk_bf16_f32 v56, v79, v81
	v_cvt_pk_bf16_f32 v57, v83, v244
	v_add_f32_e32 v36, v78, v36
	v_exp_f32_e32 v51, v65
	s_waitcnt lgkmcnt(0)
	v_mfma_f32_32x32x16_bf16 v[20:35], v[58:61], v[54:57], v[20:35]
	ds_read_b64_tr_b16 v[58:59], v228 offset:38976
	ds_read_b64_tr_b16 v[60:61], v228 offset:40512
	v_add_f32_e32 v36, v80, v36
	v_exp_f32_e32 v52, v66
	s_waitcnt lgkmcnt(0)
	v_mfma_f32_32x32x16_bf16 v[4:19], v[58:61], v[54:57], v[4:19]
	ds_read_b64_tr_b16 v[58:59], v228 offset:41984
	ds_read_b64_tr_b16 v[60:61], v228 offset:43520
	v_cvt_pk_bf16_f32 v54, v68, v69
	v_cvt_pk_bf16_f32 v55, v70, v74
	v_cvt_pk_bf16_f32 v56, v76, v78
	v_cvt_pk_bf16_f32 v57, v80, v82
	v_add_f32_e32 v36, v82, v36
	s_waitcnt lgkmcnt(0)
	v_mfma_f32_32x32x16_bf16 v[20:35], v[58:61], v[54:57], v[20:35]
	ds_read_b64_tr_b16 v[58:59], v228 offset:42048
	ds_read_b64_tr_b16 v[60:61], v228 offset:43584
	v_exp_f32_e32 v43, v43
	v_exp_f32_e32 v45, v45
	v_exp_f32_e32 v47, v62
	v_exp_f32_e32 v48, v63
	v_exp_f32_e32 v49, v64
	v_exp_f32_e32 v50, v67
	s_waitcnt lgkmcnt(0)
	v_mfma_f32_32x32x16_bf16 v[4:19], v[58:61], v[54:57], v[4:19]
	ds_read_b64_tr_b16 v[58:59], v228 offset:45056
	ds_read_b64_tr_b16 v[60:61], v228 offset:46592
	v_cvt_pk_bf16_f32 v54, v39, v37
	v_cvt_pk_bf16_f32 v55, v38, v40
	v_cvt_pk_bf16_f32 v56, v41, v42
	v_cvt_pk_bf16_f32 v57, v44, v46
	v_add_f32_e32 v36, v39, v36
	v_add_f32_e32 v36, v37, v36
	s_waitcnt lgkmcnt(0)
	v_mfma_f32_32x32x16_bf16 v[20:35], v[58:61], v[54:57], v[20:35]
	ds_read_b64_tr_b16 v[58:59], v228 offset:45120
	ds_read_b64_tr_b16 v[60:61], v228 offset:46656
	v_add_f32_e32 v36, v38, v36
	v_add_f32_e32 v36, v40, v36
	v_add_f32_e32 v36, v41, v36
	v_add_f32_e32 v36, v42, v36
	v_add_f32_e32 v36, v44, v36
	v_add_f32_e32 v36, v46, v36
	s_waitcnt lgkmcnt(0)
	v_mfma_f32_32x32x16_bf16 v[4:19], v[58:61], v[54:57], v[4:19]
	ds_read_b64_tr_b16 v[58:59], v228 offset:48128
	ds_read_b64_tr_b16 v[60:61], v228 offset:49664
	v_cvt_pk_bf16_f32 v54, v43, v45
	v_cvt_pk_bf16_f32 v55, v47, v48
	v_cvt_pk_bf16_f32 v56, v49, v51
	v_cvt_pk_bf16_f32 v57, v52, v50
	v_add_f32_e32 v36, v43, v36
	v_add_f32_e32 v36, v45, v36
	s_waitcnt lgkmcnt(0)
	v_mfma_f32_32x32x16_bf16 v[20:35], v[58:61], v[54:57], v[20:35]
	ds_read_b64_tr_b16 v[58:59], v228 offset:48192
	ds_read_b64_tr_b16 v[60:61], v228 offset:49728
	v_add_f32_e32 v36, v47, v36
	v_add_f32_e32 v36, v48, v36
	v_add_f32_e32 v36, v49, v36
	v_add_f32_e32 v36, v51, v36
	v_add_f32_e32 v36, v52, v36
	v_add_f32_e32 v36, v50, v36
	s_waitcnt lgkmcnt(0)
	v_mfma_f32_32x32x16_bf16 v[4:19], v[58:61], v[54:57], v[4:19]
	v_add_f32_e32 v133, v133, v36
	s_cbranch_scc0 .LBB0_635
